# start-time stagger of CUs sharing operand tiles in layer-0 proj GEMM
# baseline (speedup 1.0000x reference)
.LBB0_326:
.LBB0_327:
	s_lshr_b32 s98, s96, 3
	s_and_b32 s99, s98, 7
	s_lshr_b32 s98, s98, 3
	s_add_u32 s98, s98, s99
	s_cmp_eq_u32 s98, 0
	s_cbranch_scc1 .Lstg_done_p2
.Lstg_loop_p2:
	s_sleep 32
	s_sub_u32 s98, s98, 1
	s_cmp_lg_u32 s98, 0
	s_cbranch_scc1 .Lstg_loop_p2
.Lstg_done_p2:
	s_mov_b32 s33, s96
	v_mov_b32_e32 v11, v154
	s_cmpk_gt_i32 s33, 0x5ff
	v_readfirstlane_b32 s4, v11
	s_cbranch_scc1 .LBB0_357
	v_lshlrev_b32_e32 v1, 4, v11
	v_add_u32_e32 v2, 0x2000, v1
	v_ashrrev_i32_e32 v3, 31, v2
	v_lshrrev_b32_e32 v3, 22, v3
	v_add_u32_e32 v3, v2, v3
	v_ashrrev_i32_e32 v10, 10, v3
	v_mul_i32_i24_e32 v3, 0x400, v10
	v_sub_u32_e32 v2, v2, v3
	v_lshrrev_b32_e32 v3, 4, v2
	v_bitop3_b32 v2, v3, v2, 32 bitop3:0x6c
	v_ashrrev_i32_e32 v3, 31, v2
	v_lshrrev_b32_e32 v3, 26, v3
	v_add_u32_e32 v3, v2, v3
	v_lshlrev_b32_e32 v4, 3, v10
	v_ashrrev_i32_e32 v12, 6, v3
	v_and_b32_e32 v4, -16, v4
	v_add_u32_e32 v4, v12, v4
	v_and_b32_e32 v5, 3, v12
	s_mov_b32 s0, 0xfffe0
	v_lshrrev_b32_e32 v6, 2, v4
	v_lshlrev_b32_e32 v7, 1, v4
	v_and_b32_e32 v3, 0xc0, v3
	v_and_or_b32 v5, v4, s0, v5
	v_and_b32_e32 v6, 4, v6
	v_and_b32_e32 v7, 24, v7
	v_sub_u32_e32 v2, v2, v3
	v_mov_b32_e32 v3, 1
	v_or3_b32 v5, v5, v6, v7
	v_lshlrev_b32_e32 v6, 5, v10
	v_ashrrev_i16_sdwa v2, v3, sext(v2) dst_sel:DWORD dst_unused:UNUSED_PAD src0_sel:DWORD src1_sel:BYTE_0
	v_and_b32_e32 v6, 32, v6
	v_bfe_i32 v13, v2, 0, 16
	v_add_lshl_u32 v2, v6, v13, 1
	v_lshl_add_u32 v130, v5, 12, v2
	v_lshl_add_u32 v132, v4, 12, v2
	v_bfe_i32 v2, v11, 27, 1
	v_lshrrev_b32_e32 v2, 22, v2
	v_add_u32_e32 v2, v1, v2
	v_and_b32_e32 v2, 0xfffffc00, v2
	v_sub_u32_e32 v1, v1, v2
	v_lshrrev_b32_e32 v2, 4, v1
	v_bitop3_b32 v2, v2, v1, 32 bitop3:0x6c
	v_ashrrev_i32_e32 v1, 31, v1
	v_lshrrev_b32_e32 v1, 26, v1
	v_add_u32_e32 v1, v2, v1
	v_ashrrev_i32_e32 v14, 6, v1
	v_ashrrev_i32_e32 v1, 31, v11
	v_lshrrev_b32_e32 v1, 26, v1
	v_add_u32_e32 v1, v11, v1
	v_ashrrev_i32_e32 v15, 6, v1
	v_lshlrev_b32_e32 v1, 3, v15
	s_add_u32 s44, s90, 0x11918000
	v_and_b32_e32 v1, -16, v1
	s_addc_u32 s45, s91, 0
	v_add_u32_e32 v1, v14, v1
	v_and_b32_e32 v4, 3, v14
	s_ashr_i32 s47, s33, 31
	v_and_or_b32 v4, v1, s0, v4
	s_lshr_b32 s0, s47, 29
	s_add_i32 s0, s33, s0
	s_ashr_i32 s6, s4, 6
	s_ashr_i32 s1, s0, 3
	s_and_b32 s0, s0, -8
	s_ashr_i32 s5, s4, 8
	s_lshl_b32 s46, s6, 10
	s_sub_i32 s0, s33, s0
	s_cmp_lt_i32 s0, 0
	s_movk_i32 s48, 0xc1
	s_cselect_b32 s2, s48, 0xc0
	s_mul_i32 s0, s2, s0
	s_add_i32 s0, s0, s1
	s_mul_hi_i32 s1, s0, 0x2aaaaaab
	s_lshr_b32 s2, s1, 31
	s_ashr_i32 s1, s1, 6
	s_add_i32 s1, s1, s2
	s_lshl_b32 s2, s1, 3
	s_mulk_i32 s1, 0x180
	s_sub_i32 s0, s0, s1
	s_bfe_u32 s1, s0, 0x3001c
	s_add_i32 s1, s0, s1
	s_sext_i32_i16 s3, s1
	s_and_b32 s1, s1, 0xfff8
	s_sub_i32 s0, s0, s1
	s_sext_i32_i16 s0, s0
	s_ashr_i32 s66, s3, 3
	s_add_i32 s65, s2, s0
	s_sub_i32 s0, s66, 20
	s_cmp_lt_u32 s0, 12
	s_cselect_b64 s[0:1], -1, 0
	s_and_b64 s[2:3], s[0:1], exec
	s_cselect_b32 s2, s66, s65
	s_cselect_b32 s7, s91, s45
	s_cselect_b32 s8, s90, s44
	s_ashr_i32 s3, s2, 31
	s_lshl_b64 s[2:3], s[2:3], 20
	s_add_u32 s30, s8, s2
	v_lshrrev_b32_e32 v5, 2, v1
	v_lshlrev_b32_e32 v6, 1, v1
	s_addc_u32 s31, s7, s3
	v_and_b32_e32 v5, 4, v5
	v_and_b32_e32 v6, 24, v6
	s_and_b64 s[2:3], s[0:1], exec
	v_or3_b32 v4, v4, v5, v6
	v_mul_i32_i24_e32 v6, 64, v14
	s_cselect_b32 s2, s65, s66
	v_sub_u32_e32 v2, v2, v6
	s_cselect_b32 s7, s45, s91
	s_cselect_b32 s8, s44, s90
	s_ashr_i32 s3, s2, 31
	v_lshlrev_b32_e32 v5, 5, v15
	v_ashrrev_i16_sdwa v2, v3, sext(v2) dst_sel:DWORD dst_unused:UNUSED_PAD src0_sel:DWORD src1_sel:BYTE_0
	s_lshl_b64 s[2:3], s[2:3], 20
	v_and_b32_e32 v5, 32, v5
	v_bfe_i32 v16, v2, 0, 16
	s_add_u32 s38, s8, s2
	v_add_lshl_u32 v2, v5, v16, 1
	s_addc_u32 s39, s7, s3
	s_add_i32 s49, s46, 0
	v_lshl_add_u32 v134, v4, 12, v2
	s_add_i32 m0, s49, 0x10000
	v_lshl_add_u32 v136, v1, 12, v2
	global_load_lds_dwordx4 v134, s[38:39]
	s_add_i32 m0, s49, 0x12000
	s_add_u32 s2, s38, 0x80000
	global_load_lds_dwordx4 v130, s[38:39]
	s_addc_u32 s3, s39, 0
	s_add_i32 m0, s49, 0x14000
	s_add_i32 s50, s49, 0x2000
	global_load_lds_dwordx4 v134, s[2:3]
	s_add_i32 m0, s49, 0x16000
	v_mov_b32_e32 v135, 0
	global_load_lds_dwordx4 v130, s[2:3]
	s_mov_b32 m0, s49
	s_add_u32 s2, s30, 0x80000
	global_load_lds_dwordx4 v136, s[30:31]
	s_mov_b32 m0, s50
	s_addc_u32 s3, s31, 0
	s_add_i32 s51, s49, 0x4000
	global_load_lds_dwordx4 v132, s[30:31]
	s_mov_b32 m0, s51
	s_add_i32 s52, s49, 0x6000
	global_load_lds_dwordx4 v136, s[2:3]
	s_mov_b32 m0, s52
	v_mov_b32_e32 v131, v135
	global_load_lds_dwordx4 v132, s[2:3]
	v_mov_b32_e32 v137, v135
	v_mov_b32_e32 v133, v135
	s_cmp_eq_u32 s5, 1
	s_mov_b32 s42, 0
	v_lshl_add_u64 v[8:9], s[38:39], 0, v[134:135]
	v_lshl_add_u64 v[6:7], s[38:39], 0, v[130:131]
	v_lshl_add_u64 v[4:5], s[30:31], 0, v[136:137]
	v_lshl_add_u64 v[2:3], s[30:31], 0, v[132:133]
	s_cselect_b64 s[2:3], -1, 0
	s_cmp_lg_u32 s5, 1
	s_movk_i32 s53, 0x6000
	s_cbranch_scc1 .LBB0_330
	s_barrier

	.amdhsa_kernel _Z10fwd_kernel6Params
		.amdhsa_group_segment_fixed_size 0
		.amdhsa_private_segment_fixed_size 0
		.amdhsa_kernarg_size 520
		.amdhsa_user_sgpr_count 2
		.amdhsa_user_sgpr_dispatch_ptr 0
		.amdhsa_user_sgpr_queue_ptr 0
		.amdhsa_user_sgpr_kernarg_segment_ptr 1
		.amdhsa_user_sgpr_dispatch_id 0
		.amdhsa_user_sgpr_kernarg_preload_length 0
		.amdhsa_user_sgpr_kernarg_preload_offset 0
		.amdhsa_user_sgpr_private_segment_size 0
		.amdhsa_uses_dynamic_stack 0
		.amdhsa_enable_private_segment 0
		.amdhsa_system_sgpr_workgroup_id_x 1
		.amdhsa_system_sgpr_workgroup_id_y 0
		.amdhsa_system_sgpr_workgroup_id_z 0
		.amdhsa_system_sgpr_workgroup_info 0
		.amdhsa_system_vgpr_workitem_id 2
		.amdhsa_next_free_vgpr 233
		.amdhsa_next_free_sgpr 100
		.amdhsa_accum_offset 236
		.amdhsa_reserve_vcc 1
		.amdhsa_float_round_mode_32 0
		.amdhsa_float_round_mode_16_64 0
		.amdhsa_float_denorm_mode_32 3
		.amdhsa_float_denorm_mode_16_64 3
		.amdhsa_dx10_clamp 1
		.amdhsa_ieee_mode 1
		.amdhsa_fp16_overflow 0
		.amdhsa_tg_split 0
		.amdhsa_exception_fp_ieee_invalid_op 0
		.amdhsa_exception_fp_denorm_src 0
		.amdhsa_exception_fp_ieee_div_zero 0
		.amdhsa_exception_fp_ieee_overflow 0
		.amdhsa_exception_fp_ieee_underflow 0
		.amdhsa_exception_fp_ieee_inexact 0
		.amdhsa_exception_int_div_zero 0
	.end_amdhsa_kernel

amdhsa.kernels:
  - .agpr_count:     0
    .args:
      - .offset:         0
        .size:           264
        .value_kind:     by_value
      - .offset:         264
        .size:           4
        .value_kind:     hidden_block_count_x
      - .offset:         268
        .size:           4
        .value_kind:     hidden_block_count_y
      - .offset:         272
        .size:           4
        .value_kind:     hidden_block_count_z
      - .offset:         276
        .size:           2
        .value_kind:     hidden_group_size_x
      - .offset:         278
        .size:           2
        .value_kind:     hidden_group_size_y
      - .offset:         280
        .size:           2
        .value_kind:     hidden_group_size_z
      - .offset:         282
        .size:           2
        .value_kind:     hidden_remainder_x
      - .offset:         284
        .size:           2
        .value_kind:     hidden_remainder_y
      - .offset:         286
        .size:           2
        .value_kind:     hidden_remainder_z
      - .offset:         304
        .size:           8
        .value_kind:     hidden_global_offset_x
      - .offset:         312
        .size:           8
        .value_kind:     hidden_global_offset_y
      - .offset:         320
        .size:           8
        .value_kind:     hidden_global_offset_z
      - .offset:         328
        .size:           2
        .value_kind:     hidden_grid_dims
      - .offset:         352
        .size:           8
        .value_kind:     hidden_multigrid_sync_arg
      - .offset:         384
        .size:           4
        .value_kind:     hidden_dynamic_lds_size
    .group_segment_fixed_size: 0
    .kernarg_segment_align: 8
    .kernarg_segment_size: 520
    .language:       OpenCL C
    .language_version:
      - 2
      - 0
    .max_flat_workgroup_size: 512
    .name:           _Z10fwd_kernel6Params
    .private_segment_fixed_size: 0
    .sgpr_count:     106
    .sgpr_spill_count: 105
    .symbol:         _Z10fwd_kernel6Params.kd
    .uniform_work_group_size: 1
    .uses_dynamic_stack: false
    .vgpr_count:     233
    .vgpr_spill_count: 0
    .wavefront_size: 64
